# M3 readout: 16 o-gate loads issued together (row addr = row0 + q*stride) instead of 8 serialized load/store round trips
# speedup vs baseline: 1.0091x; 1.0001x over previous
; #define MFMA16(a, b, c) __builtin_amdgcn_mfma_f32_16x16x32_bf16(a, b, c, 0, 0, 0)
; __device__ __forceinline__ void m3_phase(const Params& p, char* smem) {
;     ...
;       {
;         const int mi = w & 3, nh = w >> 2;
;         f32x4 a1[4], a2[4];
; #pragma unroll
;         for (int q = 0; q < 4; ++q) { a1[q] = (f32x4){0.f, 0.f, 0.f, 0.f}; a2[q] = (f32x4){0.f, 0.f, 0.f, 0.f}; }
; #pragma unroll
;         for (int ks = 0; ks < 2; ++ks) {
;           bf16x8 a = *(const bf16x8*)(Sw + (mi * 16 + fr) * 72 + ks * 32 + fq * 8);
; #pragma unroll
;           for (int q = 0; q < 4; ++q) {
;             bf16x8 bb = *(const bf16x8*)(Vt + ((nh * 4 + q) * 16 + fr) * 72 + ks * 32 + fq * 8);
;             a1[q] = MFMA16(a, bb, a1[q]);
;           }
;         }
; #pragma unroll
;         for (int ks = 0; ks < 4; ++ks) {
;           bf16x8 a = *(const bf16x8*)(Qs + (mi * 16 + fr) * 136 + ks * 32 + fq * 8);
; #pragma unroll
;           for (int q = 0; q < 4; ++q) {
;             bf16x8 bb = *(const bf16x8*)(Cs + ((nh * 4 + q) * 16 + fr) * 136 + ks * 32 + fq * 8);
;             a2[q] = MFMA16(a, bb, a2[q]);
;           }
;         }
; #pragma unroll
;         for (int jj = 0; jj < 4; ++jj) {
;           int t = mi * 16 + fq * 4 + jj;
;           float wi = wint[t];
;           float den = denp[t] + denp[64 + t] + wi * qn[t];
;           float inv = 1.0f / fmaxf(fabsf(den), emt[t]);
;           int tl = (dir == 0) ? t : (63 - t);
; #pragma unroll
;           for (int q = 0; q < 4; ++q) {
;             int v = (nh * 4 + q) * 16 + fr;
;             float hv = (a1[q][jj] + wi * a2[q][jj]) * inv;
;             if (dir == 0) hs[tl * 132 + v] = hv; else hs[tl * 132 + v] += hv;
;           }
;         }
.LBB0_484:
	s_or_b64 exec, exec, s[2:3]
	s_waitcnt lgkmcnt(0)
	s_barrier
	ds_read_b128 v[0:3], v59
	ds_read_b128 v[4:7], v142 offset:34816
	ds_read_b128 v[8:11], v142 offset:37120
	ds_read_b128 v[12:15], v142 offset:39424
	s_waitcnt lgkmcnt(0)
	v_mfma_f32_16x16x32_bf16 v[20:23], v[0:3], v[12:15], 0
	ds_read_b128 v[12:15], v142 offset:41728
	s_mov_b64 s[14:15], 0x7291140
	s_add_u32 s94, s5, s30
	v_mfma_f32_16x16x32_bf16 v[4:7], v[0:3], v[4:7], 0
	s_addc_u32 s95, s6, 0
	s_brev_b32 s16, 60
	s_mov_b32 s12, 0x800000
	v_mfma_f32_16x16x32_bf16 v[8:11], v[0:3], v[8:11], 0
	s_add_i32 s4, s4, s80
	s_sub_i32 s10, s10, s80
	s_movk_i32 s84, 0x1600
	s_waitcnt lgkmcnt(0)
	v_mfma_f32_16x16x32_bf16 v[0:3], v[0:3], v[12:15], 0
	ds_read_b128 v[24:27], v59 offset:64
	ds_read_b128 v[12:15], v142 offset:34880
	s_cmpk_gt_i32 s4, 0x41f
	s_waitcnt lgkmcnt(0)
	v_mfma_f32_16x16x32_bf16 v[12:15], v[24:27], v[12:15], v[4:7]
	s_nop 2
	ds_read_b128 v[4:7], v142 offset:37184
	s_waitcnt lgkmcnt(0)
	v_mfma_f32_16x16x32_bf16 v[16:19], v[24:27], v[4:7], v[8:11]
	ds_read_b128 v[4:7], v142 offset:39488
	s_nop 1
	ds_read_b128 v[8:11], v142 offset:41792
	s_waitcnt lgkmcnt(1)
	v_mfma_f32_16x16x32_bf16 v[4:7], v[24:27], v[4:7], v[20:23]
	s_waitcnt lgkmcnt(0)
	v_mfma_f32_16x16x32_bf16 v[0:3], v[24:27], v[8:11], v[0:3]
	ds_read_b128 v[8:11], v52
	ds_read_b128 v[20:23], v150 offset:53248
	ds_read_b128 v[24:27], v150 offset:57600
	ds_read_b128 v[146:149], v143 offset:61952
	ds_read_b128 v[28:31], v150 offset:61952
	s_waitcnt lgkmcnt(3)
	v_mfma_f32_16x16x32_bf16 v[20:23], v[8:11], v[20:23], 0
	s_waitcnt lgkmcnt(2)
	v_mfma_f32_16x16x32_bf16 v[24:27], v[8:11], v[24:27], 0
	s_waitcnt lgkmcnt(0)
	v_mfma_f32_16x16x32_bf16 v[28:31], v[8:11], v[28:31], 0
	v_mfma_f32_16x16x32_bf16 v[8:11], v[8:11], v[146:149], 0
	ds_read_b128 v[146:149], v52 offset:64
	ds_read_b128 v[152:155], v150 offset:53312
	s_waitcnt lgkmcnt(0)
	v_mfma_f32_16x16x32_bf16 v[20:23], v[146:149], v[152:155], v[20:23]
	ds_read_b128 v[152:155], v150 offset:57664
	s_waitcnt lgkmcnt(0)
	v_mfma_f32_16x16x32_bf16 v[24:27], v[146:149], v[152:155], v[24:27]
	ds_read_b128 v[152:155], v150 offset:62016
	s_waitcnt lgkmcnt(0)
	v_mfma_f32_16x16x32_bf16 v[28:31], v[146:149], v[152:155], v[28:31]
	ds_read_b128 v[152:155], v143 offset:62016
	s_waitcnt lgkmcnt(0)
	v_mfma_f32_16x16x32_bf16 v[8:11], v[146:149], v[152:155], v[8:11]
	ds_read_b128 v[146:149], v52 offset:128
	ds_read_b128 v[152:155], v150 offset:53376
	s_waitcnt lgkmcnt(0)
	v_mfma_f32_16x16x32_bf16 v[20:23], v[146:149], v[152:155], v[20:23]
	ds_read_b128 v[152:155], v150 offset:57728
	s_waitcnt lgkmcnt(0)
	v_mfma_f32_16x16x32_bf16 v[24:27], v[146:149], v[152:155], v[24:27]
	ds_read_b128 v[152:155], v150 offset:62080
	s_waitcnt lgkmcnt(0)
	v_mfma_f32_16x16x32_bf16 v[152:155], v[146:149], v[152:155], v[28:31]
	s_nop 2
	ds_read_b128 v[28:31], v143 offset:62080
	s_waitcnt lgkmcnt(0)
	v_mfma_f32_16x16x32_bf16 v[8:11], v[146:149], v[28:31], v[8:11]
	ds_read_b128 v[146:149], v52 offset:192
	ds_read_b128 v[28:31], v150 offset:53440
	s_waitcnt lgkmcnt(0)
	v_mfma_f32_16x16x32_bf16 v[28:31], v[146:149], v[28:31], v[20:23]
	s_nop 2
	ds_read_b128 v[20:23], v150 offset:57792
	s_waitcnt lgkmcnt(0)
	v_mfma_f32_16x16x32_bf16 v[24:27], v[146:149], v[20:23], v[24:27]
	ds_read_b128 v[20:23], v150 offset:62144
	s_waitcnt lgkmcnt(0)
	v_mfma_f32_16x16x32_bf16 v[20:23], v[146:149], v[20:23], v[152:155]
	s_nop 2
	ds_read_b128 v[150:153], v143 offset:62144
	s_waitcnt lgkmcnt(0)
	v_mfma_f32_16x16x32_bf16 v[8:11], v[146:149], v[150:153], v[8:11]
	ds_read_b32 v148, v98
	ds_read2st64_b32 v[146:147], v99 offset1:1
	s_waitcnt lgkmcnt(1)
	v_fma_f32 v12, v28, v148, v12
	s_waitcnt lgkmcnt(0)
	v_add_f32_e32 v146, v146, v147
	ds_read_b32 v147, v100
	v_fma_f32 v16, v24, v148, v16
	v_fma_f32 v4, v20, v148, v4
	v_fma_f32 v0, v148, v8, v0
	s_waitcnt lgkmcnt(0)
	v_fmac_f32_e32 v146, v148, v147
	ds_read_b32 v147, v101
	s_waitcnt lgkmcnt(0)
	v_max_f32_e32 v147, v147, v147
	v_max_f32_e64 v146, |v146|, v147
	v_div_scale_f32 v147, s[2:3], v146, v146, 1.0
	v_rcp_f32_e32 v149, v147
	s_nop 0
	v_fma_f32 v150, -v147, v149, 1.0
	v_fmac_f32_e32 v149, v150, v149
	v_div_scale_f32 v150, vcc, 1.0, v146, 1.0
	v_mul_f32_e32 v151, v150, v149
	v_fma_f32 v152, -v147, v151, v150
	v_fmac_f32_e32 v151, v152, v149
	v_fma_f32 v147, -v147, v151, v150
	v_div_fmas_f32 v147, v147, v149, v151
	v_div_fixup_f32 v149, v147, v146, 1.0
	ds_read2_b32 v[146:147], v118 offset1:16
	s_waitcnt lgkmcnt(0)
	v_fma_f32 v12, v12, v149, v146
	v_fmac_f32_e32 v147, v16, v149
	ds_write2_b32 v118, v12, v147 offset1:16
	ds_read2_b32 v[146:147], v118 offset0:32 offset1:48
	s_waitcnt lgkmcnt(0)
	v_fma_f32 v4, v4, v149, v146
	v_fmac_f32_e32 v147, v0, v149
	ds_write2_b32 v118, v4, v147 offset0:32 offset1:48
	ds_read_b32 v0, v103
	ds_read_b32 v4, v104
	ds_read_b32 v8, v105
	ds_read2st64_b32 v[146:147], v106 offset1:1
	s_waitcnt lgkmcnt(2)
	v_max_f32_e32 v4, v4, v4
	s_waitcnt lgkmcnt(0)
	v_add_f32_e32 v12, v147, v146
	v_fmac_f32_e32 v12, v0, v8
	v_max_f32_e64 v4, |v12|, v4
	v_div_scale_f32 v8, s[2:3], v4, v4, 1.0
	v_rcp_f32_e32 v12, v8
	s_nop 0
	v_fma_f32 v16, -v8, v12, 1.0
	v_fmac_f32_e32 v12, v16, v12
	v_div_scale_f32 v16, vcc, 1.0, v4, 1.0
	v_mul_f32_e32 v20, v16, v12
	v_fma_f32 v24, -v8, v20, v16
	v_fmac_f32_e32 v20, v24, v12
	v_fma_f32 v8, -v8, v20, v16
	v_div_fmas_f32 v8, v8, v12, v20
	v_div_fixup_f32 v8, v8, v4, 1.0
	v_fma_f32 v4, v29, v0, v13
	ds_read2_b32 v[12:13], v119 offset1:16
	s_waitcnt lgkmcnt(0)
	v_fma_f32 v4, v4, v8, v12
	v_fma_f32 v12, v25, v0, v17
	v_fmac_f32_e32 v13, v12, v8
	ds_write2_b32 v119, v4, v13 offset1:16
	v_fma_f32 v12, v21, v0, v5
	ds_read2_b32 v[4:5], v119 offset0:32 offset1:48
	v_fma_f32 v0, v9, v0, v1
	s_waitcnt lgkmcnt(0)
;   __host__ __device__ __forceinline__ bf16_t* ACT() const { return (bf16_t*)(wsl() + OFF_ACT); }
; __device__ __forceinline__ float bf2f(bf16_t h) { return __uint_as_float(((uint32_t)h) << 16); }
; __device__ __forceinline__ void m3_phase(const Params& p, char* smem) {
;     ...
; #pragma unroll
;         for (int jj = 0; jj < 4; ++jj) {
;           int t = mi * 16 + fq * 4 + jj;
;           float wi = wint[t];
;           float den = denp[t] + denp[64 + t] + wi * qn[t];
;           float inv = 1.0f / fmaxf(fabsf(den), emt[t]);
;           int tl = (dir == 0) ? t : (63 - t);
; #pragma unroll
;           for (int q = 0; q < 4; ++q) {
;             int v = (nh * 4 + q) * 16 + fr;
;             float hv = (a1[q][jj] + wi * a2[q][jj]) * inv;
;             if (dir == 0) hs[tl * 132 + v] = hv; else hs[tl * 132 + v] += hv;
;           }
;         }
;       }
;       __syncthreads();
;     }
;     for (int q = 0; q < 8; ++q) {
;       int tl = w * 8 + q;
;       float v0 = hs[tl * 132 + lane], v1 = hs[tl * 132 + 64 + lane];
;       float ss = wave_sum(v0 * v0 + v1 * v1);
;       float rstd = rsqrtf(ss * (1.0f / 128.0f) + 1e-6f);
;       int row = rowbase + c * 64 + tl;
;       const bf16_t* po = p.ACT() + (size_t)row * PW + 2208 + h * 128;
;       float o0 = bf2f(po[lane]), o1 = bf2f(po[64 + lane]);
	v_fma_f32 v4, v12, v8, v4
	v_fmac_f32_e32 v5, v0, v8
	ds_write2_b32 v119, v4, v5 offset0:32 offset1:48
	ds_read_b32 v4, v108
	ds_read_b32 v5, v109
	ds_read_b32 v8, v110
	ds_read2st64_b32 v[0:1], v111 offset1:1
	s_waitcnt lgkmcnt(3)
	v_fma_f32 v6, v22, v4, v6
	v_fma_f32 v2, v10, v4, v2
	s_waitcnt lgkmcnt(0)
	v_add_f32_e32 v0, v1, v0
	v_fmac_f32_e32 v0, v4, v8
	v_max_f32_e32 v1, v5, v5
	v_max_f32_e64 v0, |v0|, v1
	v_div_scale_f32 v1, s[2:3], v0, v0, 1.0
	v_rcp_f32_e32 v5, v1
	s_nop 0
	v_fma_f32 v8, -v1, v5, 1.0
	v_fmac_f32_e32 v5, v8, v5
	v_div_scale_f32 v8, vcc, 1.0, v0, 1.0
	v_mul_f32_e32 v9, v8, v5
	v_fma_f32 v12, -v1, v9, v8
	v_fmac_f32_e32 v9, v12, v5
	v_fma_f32 v1, -v1, v9, v8
	v_div_fmas_f32 v1, v1, v5, v9
	v_div_fixup_f32 v5, v1, v0, 1.0
	ds_read2_b32 v[0:1], v120 offset1:16
	v_fma_f32 v8, v30, v4, v14
	s_waitcnt lgkmcnt(0)
	v_fma_f32 v0, v8, v5, v0
	v_fma_f32 v8, v26, v4, v18
	v_fmac_f32_e32 v1, v8, v5
	ds_write2_b32 v120, v0, v1 offset1:16
	ds_read2_b32 v[0:1], v120 offset0:32 offset1:48
	s_waitcnt lgkmcnt(0)
	v_fma_f32 v0, v6, v5, v0
	v_fmac_f32_e32 v1, v2, v5
	ds_write2_b32 v120, v0, v1 offset0:32 offset1:48
	ds_read_b32 v2, v113
	ds_read_b32 v4, v114
	ds_read_b32 v5, v115
	ds_read2st64_b32 v[0:1], v116 offset1:1
	s_waitcnt lgkmcnt(3)
	v_fmac_f32_e32 v15, v31, v2
	v_fmac_f32_e32 v19, v27, v2
	v_fmac_f32_e32 v7, v23, v2
	s_waitcnt lgkmcnt(0)
	v_add_f32_e32 v0, v1, v0
	v_fmac_f32_e32 v0, v2, v5
	v_max_f32_e32 v1, v4, v4
	v_max_f32_e64 v0, |v0|, v1
	v_div_scale_f32 v1, s[2:3], v0, v0, 1.0
	v_rcp_f32_e32 v4, v1
	v_fmac_f32_e32 v3, v11, v2
	v_add_u32_e32 v2, s11, v66
	s_mov_b32 s11, 0x7291000
	v_fma_f32 v5, -v1, v4, 1.0
	v_fmac_f32_e32 v4, v5, v4
	v_div_scale_f32 v5, vcc, 1.0, v0, 1.0
	v_mul_f32_e32 v6, v5, v4
	v_fma_f32 v8, -v1, v6, v5
	v_fmac_f32_e32 v6, v8, v4
	v_fma_f32 v1, -v1, v6, v5
	v_div_fmas_f32 v1, v1, v4, v6
	v_div_fixup_f32 v4, v1, v0, 1.0
	ds_read2_b32 v[0:1], v121 offset1:16
	s_waitcnt lgkmcnt(0)
	v_fma_f32 v0, v15, v4, v0
	v_fmac_f32_e32 v1, v19, v4
	ds_write2_b32 v121, v0, v1 offset1:16
	ds_read2_b32 v[0:1], v121 offset0:32 offset1:48
	s_waitcnt lgkmcnt(0)
	v_fma_f32 v0, v7, v4, v0
	v_fmac_f32_e32 v1, v3, v4
	ds_write2_b32 v121, v0, v1 offset0:32 offset1:48
	v_or_b32_e32 v0, s13, v34
	v_lshlrev_b32_e32 v0, 2, v0
	s_waitcnt lgkmcnt(0)
	s_barrier
	global_load_dword v13, v0, s[86:87]
	global_load_dword v12, v0, s[86:87] offset:256
	v_mov_b64_e32 v[0:1], s[88:89]
	s_movk_i32 s13, 0x1600
	v_mad_i64_i32 v[6:7], s[2:3], v2, s13, v[0:1]
	v_lshl_add_u64 v[6:7], v[6:7], 0, s[30:31]
	v_lshl_add_u64 v[6:7], v[6:7], 0, v[166:167]
	v_lshl_add_u64 v[10:11], v[6:7], 0, s[14:15]
	v_add_co_u32_e32 v6, vcc, s11, v6
	ds_read_b32 v8, v69
	ds_read_b32 v9, v122 offset:256
	v_addc_co_u32_e32 v7, vcc, 0, v7, vcc
	v_add_co_u32_e32 v180, vcc, 0x1600, v6
	s_nop 1
	v_addc_co_u32_e32 v181, vcc, 0, v7, vcc
	global_load_ushort v182, v[180:181], off offset:320
	v_add_co_u32_e32 v180, vcc, 0x1600, v10
	s_nop 1
	v_addc_co_u32_e32 v181, vcc, 0, v11, vcc
	global_load_ushort v183, v[180:181], off offset:128
	v_add_co_u32_e32 v180, vcc, 0x2c00, v6
	s_nop 1
	v_addc_co_u32_e32 v181, vcc, 0, v7, vcc
	global_load_ushort v184, v[180:181], off offset:320
	v_add_co_u32_e32 v180, vcc, 0x2c00, v10
	s_nop 1
	v_addc_co_u32_e32 v181, vcc, 0, v11, vcc
	global_load_ushort v185, v[180:181], off offset:128
	v_add_co_u32_e32 v180, vcc, 0x4200, v6
	s_nop 1
	v_addc_co_u32_e32 v181, vcc, 0, v7, vcc
	global_load_ushort v186, v[180:181], off offset:320
	v_add_co_u32_e32 v180, vcc, 0x4200, v10
	s_nop 1
	v_addc_co_u32_e32 v181, vcc, 0, v11, vcc
	global_load_ushort v187, v[180:181], off offset:128
	v_add_co_u32_e32 v180, vcc, 0x5800, v6
	s_nop 1
	v_addc_co_u32_e32 v181, vcc, 0, v7, vcc
	global_load_ushort v188, v[180:181], off offset:320
	v_add_co_u32_e32 v180, vcc, 0x5800, v10
	s_nop 1
	v_addc_co_u32_e32 v181, vcc, 0, v11, vcc
	global_load_ushort v189, v[180:181], off offset:128
	v_add_co_u32_e32 v180, vcc, 0x6e00, v6
	s_nop 1
	v_addc_co_u32_e32 v181, vcc, 0, v7, vcc
	global_load_ushort v190, v[180:181], off offset:320
	v_add_co_u32_e32 v180, vcc, 0x6e00, v10
	s_nop 1
	v_addc_co_u32_e32 v181, vcc, 0, v11, vcc
	global_load_ushort v191, v[180:181], off offset:128
	v_add_co_u32_e32 v180, vcc, 0x8400, v6
	s_nop 1
	v_addc_co_u32_e32 v181, vcc, 0, v7, vcc
	global_load_ushort v192, v[180:181], off offset:320
	v_add_co_u32_e32 v180, vcc, 0x8400, v10
	s_nop 1
	v_addc_co_u32_e32 v181, vcc, 0, v11, vcc
	global_load_ushort v193, v[180:181], off offset:128
	v_add_co_u32_e32 v180, vcc, 0x9a00, v6
	s_nop 1
	v_addc_co_u32_e32 v181, vcc, 0, v7, vcc
	global_load_ushort v194, v[180:181], off offset:320
	v_add_co_u32_e32 v180, vcc, 0x9a00, v10
	s_nop 1
	v_addc_co_u32_e32 v181, vcc, 0, v11, vcc
	global_load_ushort v195, v[180:181], off offset:128
	global_load_ushort v6, v[6:7], off offset:320
	v_ashrrev_i32_e32 v3, 31, v2
	global_load_ushort v7, v[10:11], off offset:128
	s_waitcnt lgkmcnt(0)
	v_pk_mul_f32 v[4:5], v[8:9], v[8:9]
	s_mov_b32 s2, 0x358637bd
	v_mov_b32_e32 v17, v4
	s_waitcnt vmcnt(1)
	v_lshlrev_b32_e32 v6, 16, v6
	v_mul_f32_e32 v6, 0xbfb8aa3b, v6
	v_exp_f32_e32 v6, v6
	s_waitcnt vmcnt(0)
	v_lshlrev_b32_e32 v7, 16, v7
	v_add_f32_e32 v6, 1.0, v6
	v_rcp_f32_e32 v18, v6
	v_mul_f32_e32 v6, 0xbfb8aa3b, v7
	v_exp_f32_e32 v6, v6
	s_nop 0
	v_add_f32_e32 v6, 1.0, v6
	v_rcp_f32_e32 v19, v6
	v_lshlrev_b64 v[6:7], 11, v[2:3]
	v_lshl_add_u64 v[6:7], s[94:95], 0, v[6:7]
	v_lshl_add_u64 v[10:11], v[6:7], 0, v[166:167]
	ds_read_b32 v6, v123
	ds_read_b32 v7, v124 offset:256
	s_waitcnt lgkmcnt(0)
;   __host__ __device__ __forceinline__ bf16_t* ACT() const { return (bf16_t*)(wsl() + OFF_ACT); }
; __device__ __forceinline__ float bf2f(bf16_t h) { return __uint_as_float(((uint32_t)h) << 16); }
; __device__ __forceinline__ float sigmoidf_(float x) { return __builtin_amdgcn_rcpf(1.0f + __expf(-x)); }
; __device__ __forceinline__ void m3_phase(const Params& p, char* smem) {
;     ...
;     for (int q = 0; q < 8; ++q) {
;       int tl = w * 8 + q;
;       float v0 = hs[tl * 132 + lane], v1 = hs[tl * 132 + 64 + lane];
;       float ss = wave_sum(v0 * v0 + v1 * v1);
;       float rstd = rsqrtf(ss * (1.0f / 128.0f) + 1e-6f);
;       int row = rowbase + c * 64 + tl;
;       const bf16_t* po = p.ACT() + (size_t)row * PW + 2208 + h * 128;
;       float o0 = bf2f(po[lane]), o1 = bf2f(po[64 + lane]);
;       float y0 = v0 * rstd * p.mlstm_out_g[h * 128 + lane] * sigmoidf_(o0);
;       float y1 = v1 * rstd * p.mlstm_out_g[h * 128 + 64 + lane] * sigmoidf_(o1);
;       MIX[(size_t)row * D + 512 + h * 128 + lane] = f2bf(y0);
;       MIX[(size_t)row * D + 512 + h * 128 + 64 + lane] = f2bf(y1);
;     }
	v_pk_mul_f32 v[14:15], v[6:7], v[6:7]
	s_nop 0
	v_mov_b32_e32 v16, v14
	v_mov_b32_e32 v4, v15
	v_pk_add_f32 v[4:5], v[16:17], v[4:5]
	ds_bpermute_b32 v15, v67, v5
	ds_bpermute_b32 v14, v67, v4
	s_waitcnt lgkmcnt(0)
	v_pk_add_f32 v[4:5], v[4:5], v[14:15]
	ds_bpermute_b32 v15, v68, v5
	ds_bpermute_b32 v14, v68, v4
	s_waitcnt lgkmcnt(0)
	v_pk_add_f32 v[4:5], v[4:5], v[14:15]
	ds_bpermute_b32 v15, v56, v5
	ds_bpermute_b32 v14, v56, v4
	s_waitcnt lgkmcnt(0)
	v_pk_add_f32 v[4:5], v[4:5], v[14:15]
	ds_bpermute_b32 v15, v55, v5
	ds_bpermute_b32 v14, v55, v4
	s_waitcnt lgkmcnt(0)
	v_pk_add_f32 v[4:5], v[4:5], v[14:15]
	ds_bpermute_b32 v15, v54, v5
	ds_bpermute_b32 v14, v54, v4
	s_waitcnt lgkmcnt(0)
	v_pk_add_f32 v[4:5], v[4:5], v[14:15]
	ds_bpermute_b32 v15, v53, v5
	ds_bpermute_b32 v14, v53, v4
	s_waitcnt lgkmcnt(0)
	v_pk_add_f32 v[14:15], v[4:5], v[14:15]
	v_mov_b64_e32 v[4:5], s[2:3]
	v_pk_fma_f32 v[14:15], v[14:15], s[16:17], v[4:5] op_sel_hi:[1,0,0]
	s_nop 0
	v_mul_f32_e32 v3, 0x4b800000, v15
	v_cmp_gt_f32_e64 s[78:79], s12, v15
	v_cmp_gt_f32_e32 vcc, s12, v14
	s_nop 0
	v_cndmask_b32_e64 v3, v15, v3, s[78:79]
	v_rsq_f32_e32 v3, v3
	s_nop 0
	v_mul_f32_e32 v15, 0x45800000, v3
	v_cndmask_b32_e64 v3, v3, v15, s[78:79]
	v_mul_f32_e32 v8, v8, v3
	v_mul_f32_e32 v8, v13, v8
	v_mul_f32_e32 v8, v18, v8
	v_mul_f32_e32 v3, v9, v3
	v_mul_f32_e32 v3, v12, v3
	v_bfe_u32 v9, v8, 16, 1
	v_mul_f32_e32 v3, v19, v3
	v_add3_u32 v8, v8, v9, s28
	global_store_short_d16_hi v[10:11], v8, off offset:1024
	v_bfe_u32 v8, v3, 16, 1
	v_add3_u32 v3, v3, v8, s28
	global_store_short_d16_hi v[10:11], v3, off offset:1152
	v_mul_f32_e32 v3, 0x4b800000, v14
	v_cndmask_b32_e32 v3, v14, v3, vcc
	v_rsq_f32_e32 v3, v3
	s_nop 0
	v_mul_f32_e32 v8, 0x45800000, v3
	v_cndmask_b32_e32 v3, v3, v8, vcc
	v_add_u32_e32 v8, 1, v2
	v_mad_i64_i32 v[10:11], s[2:3], v8, s13, v[0:1]
	v_lshl_add_u64 v[10:11], v[10:11], 0, s[30:31]
	v_lshl_add_u64 v[10:11], v[10:11], 0, v[166:167]
	v_lshl_add_u64 v[14:15], v[10:11], 0, s[14:15]
	v_add_co_u32_e32 v10, vcc, s11, v10
	v_mul_f32_e32 v6, v6, v3
	s_nop 0
	v_addc_co_u32_e32 v11, vcc, 0, v11, vcc
	v_mov_b32_e32 v10, v182
	v_mul_f32_e32 v3, v7, v3
	v_mov_b32_e32 v11, v183
	v_mul_f32_e32 v6, v13, v6
	v_mul_f32_e32 v3, v12, v3
	v_ashrrev_i32_e32 v9, 31, v8
	v_lshlrev_b32_e32 v10, 16, v10
	v_mul_f32_e32 v10, 0xbfb8aa3b, v10
	v_lshlrev_b32_e32 v11, 16, v11
	v_exp_f32_e32 v10, v10
	v_mul_f32_e32 v7, 0xbfb8aa3b, v11
	v_exp_f32_e32 v7, v7
	v_add_f32_e32 v10, 1.0, v10
	v_rcp_f32_e32 v10, v10
	v_add_f32_e32 v7, 1.0, v7
	v_rcp_f32_e32 v7, v7
	v_mul_f32_e32 v6, v10, v6
	v_mul_f32_e32 v3, v7, v3
	v_bfe_u32 v7, v6, 16, 1
	v_add3_u32 v10, v6, v7, s28
	v_lshlrev_b64 v[6:7], 11, v[8:9]
	v_lshl_add_u64 v[6:7], s[94:95], 0, v[6:7]
	v_bfe_u32 v8, v3, 16, 1
	v_lshl_add_u64 v[6:7], v[6:7], 0, v[166:167]
	v_add3_u32 v3, v3, v8, s28
	global_store_short_d16_hi v[6:7], v10, off offset:1024
	global_store_short_d16_hi v[6:7], v3, off offset:1152
	v_add_u32_e32 v6, 2, v2
	v_mad_i64_i32 v[14:15], s[2:3], v6, s13, v[0:1]
	v_lshl_add_u64 v[14:15], v[14:15], 0, s[30:31]
	v_lshl_add_u64 v[14:15], v[14:15], 0, v[166:167]
	v_lshl_add_u64 v[16:17], v[14:15], 0, s[14:15]
	v_add_co_u32_e32 v14, vcc, s11, v14
	ds_read_b32 v8, v125
	ds_read_b32 v9, v126 offset:256
	v_addc_co_u32_e32 v15, vcc, 0, v15, vcc
	v_mov_b32_e32 v3, v184
	v_ashrrev_i32_e32 v7, 31, v6
	v_mov_b32_e32 v14, v185
	v_lshlrev_b64 v[6:7], 11, v[6:7]
	v_lshl_add_u64 v[6:7], s[94:95], 0, v[6:7]
	s_waitcnt lgkmcnt(0)
	v_pk_mul_f32 v[10:11], v[8:9], v[8:9]
	v_lshlrev_b32_e32 v3, 16, v3
	v_mov_b32_e32 v19, v10
	v_lshlrev_b32_e32 v14, 16, v14
	v_mul_f32_e32 v14, 0xbfb8aa3b, v14
	v_exp_f32_e32 v14, v14
	v_mul_f32_e32 v3, 0xbfb8aa3b, v3
	v_exp_f32_e32 v3, v3
	v_add_f32_e32 v14, 1.0, v14
	v_rcp_f32_e32 v20, v14
	v_lshl_add_u64 v[14:15], v[6:7], 0, v[166:167]
	ds_read_b32 v6, v127
	ds_read_b32 v7, v128 offset:256
	v_add_f32_e32 v3, 1.0, v3
	v_rcp_f32_e32 v3, v3
	s_waitcnt lgkmcnt(0)
	v_pk_mul_f32 v[16:17], v[6:7], v[6:7]
	s_nop 0
	v_mov_b32_e32 v18, v16
	v_mov_b32_e32 v10, v17
	v_pk_add_f32 v[10:11], v[18:19], v[10:11]
	ds_bpermute_b32 v17, v67, v11
	ds_bpermute_b32 v16, v67, v10
	s_waitcnt lgkmcnt(0)
	v_pk_add_f32 v[10:11], v[10:11], v[16:17]
	ds_bpermute_b32 v17, v68, v11
	ds_bpermute_b32 v16, v68, v10
	s_waitcnt lgkmcnt(0)
	v_pk_add_f32 v[10:11], v[10:11], v[16:17]
	ds_bpermute_b32 v17, v56, v11
	ds_bpermute_b32 v16, v56, v10
	s_waitcnt lgkmcnt(0)
	v_pk_add_f32 v[10:11], v[10:11], v[16:17]
	ds_bpermute_b32 v17, v55, v11
	ds_bpermute_b32 v16, v55, v10
	s_waitcnt lgkmcnt(0)
	v_pk_add_f32 v[10:11], v[10:11], v[16:17]
	ds_bpermute_b32 v17, v54, v11
	ds_bpermute_b32 v16, v54, v10
	s_waitcnt lgkmcnt(0)
	v_pk_add_f32 v[10:11], v[10:11], v[16:17]
	ds_bpermute_b32 v17, v53, v11
	ds_bpermute_b32 v16, v53, v10
	s_waitcnt lgkmcnt(0)
;   __host__ __device__ __forceinline__ bf16_t* ACT() const { return (bf16_t*)(wsl() + OFF_ACT); }
; __device__ __forceinline__ float bf2f(bf16_t h) { return __uint_as_float(((uint32_t)h) << 16); }
; __device__ __forceinline__ float sigmoidf_(float x) { return __builtin_amdgcn_rcpf(1.0f + __expf(-x)); }
; __device__ __forceinline__ void m3_phase(const Params& p, char* smem) {
;     ...
;     for (int q = 0; q < 8; ++q) {
;       int tl = w * 8 + q;
;       float v0 = hs[tl * 132 + lane], v1 = hs[tl * 132 + 64 + lane];
;       float ss = wave_sum(v0 * v0 + v1 * v1);
;       float rstd = rsqrtf(ss * (1.0f / 128.0f) + 1e-6f);
;       int row = rowbase + c * 64 + tl;
;       const bf16_t* po = p.ACT() + (size_t)row * PW + 2208 + h * 128;
;       float o0 = bf2f(po[lane]), o1 = bf2f(po[64 + lane]);
;       float y0 = v0 * rstd * p.mlstm_out_g[h * 128 + lane] * sigmoidf_(o0);
;       float y1 = v1 * rstd * p.mlstm_out_g[h * 128 + 64 + lane] * sigmoidf_(o1);
;       MIX[(size_t)row * D + 512 + h * 128 + lane] = f2bf(y0);
;       MIX[(size_t)row * D + 512 + h * 128 + 64 + lane] = f2bf(y1);
;     }
	v_pk_add_f32 v[10:11], v[10:11], v[16:17]
	s_nop 0
	v_pk_fma_f32 v[10:11], v[10:11], s[16:17], v[4:5] op_sel_hi:[1,0,0]
	s_nop 0
	v_mul_f32_e32 v16, 0x4b800000, v11
	v_cmp_gt_f32_e64 s[78:79], s12, v11
	v_cmp_gt_f32_e32 vcc, s12, v10
	s_nop 0
	v_cndmask_b32_e64 v11, v11, v16, s[78:79]
	v_rsq_f32_e32 v11, v11
	s_nop 0
	v_mul_f32_e32 v16, 0x45800000, v11
	v_cndmask_b32_e64 v11, v11, v16, s[78:79]
	v_mul_f32_e32 v8, v8, v11
	v_mul_f32_e32 v8, v13, v8
	v_mul_f32_e32 v3, v3, v8
	v_mul_f32_e32 v8, v9, v11
	v_mul_f32_e32 v8, v12, v8
	v_bfe_u32 v9, v3, 16, 1
	v_mul_f32_e32 v8, v20, v8
	v_add3_u32 v3, v3, v9, s28
	global_store_short_d16_hi v[14:15], v3, off offset:1024
	v_bfe_u32 v3, v8, 16, 1
	v_add3_u32 v3, v8, v3, s28
	global_store_short_d16_hi v[14:15], v3, off offset:1152
	v_mul_f32_e32 v3, 0x4b800000, v10
	v_cndmask_b32_e32 v3, v10, v3, vcc
	v_rsq_f32_e32 v3, v3
	s_nop 0
	v_mul_f32_e32 v8, 0x45800000, v3
	v_cndmask_b32_e32 v3, v3, v8, vcc
	v_add_u32_e32 v8, 3, v2
	v_mad_i64_i32 v[10:11], s[2:3], v8, s13, v[0:1]
	v_lshl_add_u64 v[10:11], v[10:11], 0, s[30:31]
	v_lshl_add_u64 v[10:11], v[10:11], 0, v[166:167]
	v_lshl_add_u64 v[14:15], v[10:11], 0, s[14:15]
	v_add_co_u32_e32 v10, vcc, s11, v10
	v_mul_f32_e32 v6, v6, v3
	s_nop 0
	v_addc_co_u32_e32 v11, vcc, 0, v11, vcc
	v_mov_b32_e32 v10, v186
	v_mul_f32_e32 v3, v7, v3
	v_mov_b32_e32 v11, v187
	v_mul_f32_e32 v6, v13, v6
	v_mul_f32_e32 v3, v12, v3
	v_ashrrev_i32_e32 v9, 31, v8
	v_lshlrev_b32_e32 v10, 16, v10
	v_mul_f32_e32 v10, 0xbfb8aa3b, v10
	v_lshlrev_b32_e32 v11, 16, v11
	v_exp_f32_e32 v10, v10
	v_mul_f32_e32 v7, 0xbfb8aa3b, v11
	v_exp_f32_e32 v7, v7
	v_add_f32_e32 v10, 1.0, v10
	v_rcp_f32_e32 v10, v10
	v_add_f32_e32 v7, 1.0, v7
	v_rcp_f32_e32 v7, v7
	v_mul_f32_e32 v6, v10, v6
	v_mul_f32_e32 v3, v7, v3
	v_bfe_u32 v7, v6, 16, 1
	v_add3_u32 v10, v6, v7, s28
	v_lshlrev_b64 v[6:7], 11, v[8:9]
	v_lshl_add_u64 v[6:7], s[94:95], 0, v[6:7]
	v_lshl_add_u64 v[6:7], v[6:7], 0, v[166:167]
	global_store_short_d16_hi v[6:7], v10, off offset:1024
	v_add_u32_e32 v10, 4, v2
	v_mad_i64_i32 v[14:15], s[2:3], v10, s13, v[0:1]
	v_lshl_add_u64 v[14:15], v[14:15], 0, s[30:31]
	v_bfe_u32 v8, v3, 16, 1
	v_lshl_add_u64 v[14:15], v[14:15], 0, v[166:167]
	v_add3_u32 v3, v3, v8, s28
	v_lshl_add_u64 v[16:17], v[14:15], 0, s[14:15]
	v_add_co_u32_e32 v14, vcc, s11, v14
	global_store_short_d16_hi v[6:7], v3, off offset:1152
	s_nop 0
	v_addc_co_u32_e32 v15, vcc, 0, v15, vcc
	ds_read_b32 v6, v129
	ds_read_b32 v7, v130 offset:256
	v_mov_b32_e32 v3, v188
	v_ashrrev_i32_e32 v11, 31, v10
	v_mov_b32_e32 v14, v189
	v_lshlrev_b64 v[10:11], 11, v[10:11]
	v_lshl_add_u64 v[10:11], s[94:95], 0, v[10:11]
	s_waitcnt lgkmcnt(0)
	v_pk_mul_f32 v[8:9], v[6:7], v[6:7]
	v_lshlrev_b32_e32 v3, 16, v3
	v_mov_b32_e32 v19, v8
	v_lshlrev_b32_e32 v14, 16, v14
	v_mul_f32_e32 v14, 0xbfb8aa3b, v14
	v_exp_f32_e32 v14, v14
	v_mul_f32_e32 v3, 0xbfb8aa3b, v3
	v_exp_f32_e32 v3, v3
	v_add_f32_e32 v14, 1.0, v14
	v_rcp_f32_e32 v20, v14
	v_lshl_add_u64 v[14:15], v[10:11], 0, v[166:167]
	ds_read_b32 v10, v131
	ds_read_b32 v11, v132 offset:256
	v_add_f32_e32 v3, 1.0, v3
	v_rcp_f32_e32 v3, v3
	s_waitcnt lgkmcnt(0)
	v_pk_mul_f32 v[16:17], v[10:11], v[10:11]
	s_nop 0
	v_mov_b32_e32 v18, v16
	v_mov_b32_e32 v8, v17
	v_pk_add_f32 v[8:9], v[18:19], v[8:9]
	ds_bpermute_b32 v17, v67, v9
	ds_bpermute_b32 v16, v67, v8
	s_waitcnt lgkmcnt(0)
	v_pk_add_f32 v[8:9], v[8:9], v[16:17]
	ds_bpermute_b32 v17, v68, v9
	ds_bpermute_b32 v16, v68, v8
	s_waitcnt lgkmcnt(0)
	v_pk_add_f32 v[8:9], v[8:9], v[16:17]
	ds_bpermute_b32 v17, v56, v9
	ds_bpermute_b32 v16, v56, v8
	s_waitcnt lgkmcnt(0)
	v_pk_add_f32 v[8:9], v[8:9], v[16:17]
	ds_bpermute_b32 v17, v55, v9
	ds_bpermute_b32 v16, v55, v8
	s_waitcnt lgkmcnt(0)
	v_pk_add_f32 v[8:9], v[8:9], v[16:17]
	ds_bpermute_b32 v17, v54, v9
	ds_bpermute_b32 v16, v54, v8
	s_waitcnt lgkmcnt(0)
	v_pk_add_f32 v[8:9], v[8:9], v[16:17]
	ds_bpermute_b32 v17, v53, v9
	ds_bpermute_b32 v16, v53, v8
	s_waitcnt lgkmcnt(0)
;   __host__ __device__ __forceinline__ bf16_t* ACT() const { return (bf16_t*)(wsl() + OFF_ACT); }
; __device__ __forceinline__ float bf2f(bf16_t h) { return __uint_as_float(((uint32_t)h) << 16); }
; __device__ __forceinline__ float sigmoidf_(float x) { return __builtin_amdgcn_rcpf(1.0f + __expf(-x)); }
; __device__ __forceinline__ void m3_phase(const Params& p, char* smem) {
;     ...
;     for (int q = 0; q < 8; ++q) {
;       int tl = w * 8 + q;
;       float v0 = hs[tl * 132 + lane], v1 = hs[tl * 132 + 64 + lane];
;       float ss = wave_sum(v0 * v0 + v1 * v1);
;       float rstd = rsqrtf(ss * (1.0f / 128.0f) + 1e-6f);
;       int row = rowbase + c * 64 + tl;
;       const bf16_t* po = p.ACT() + (size_t)row * PW + 2208 + h * 128;
;       float o0 = bf2f(po[lane]), o1 = bf2f(po[64 + lane]);
;       float y0 = v0 * rstd * p.mlstm_out_g[h * 128 + lane] * sigmoidf_(o0);
;       float y1 = v1 * rstd * p.mlstm_out_g[h * 128 + 64 + lane] * sigmoidf_(o1);
;       MIX[(size_t)row * D + 512 + h * 128 + lane] = f2bf(y0);
;       MIX[(size_t)row * D + 512 + h * 128 + 64 + lane] = f2bf(y1);
;     }
;     __syncthreads();
	v_pk_add_f32 v[8:9], v[8:9], v[16:17]
	s_nop 0
	v_pk_fma_f32 v[8:9], v[8:9], s[16:17], v[4:5] op_sel_hi:[1,0,0]
	s_nop 0
	v_mul_f32_e32 v16, 0x4b800000, v9
	v_cmp_gt_f32_e64 s[78:79], s12, v9
	v_cmp_gt_f32_e32 vcc, s12, v8
	s_nop 0
	v_cndmask_b32_e64 v9, v9, v16, s[78:79]
	v_rsq_f32_e32 v9, v9
	s_nop 0
	v_mul_f32_e32 v16, 0x45800000, v9
	v_cndmask_b32_e64 v9, v9, v16, s[78:79]
	v_mul_f32_e32 v6, v6, v9
	v_mul_f32_e32 v6, v13, v6
	v_mul_f32_e32 v3, v3, v6
	v_mul_f32_e32 v6, v7, v9
	v_mul_f32_e32 v6, v12, v6
	v_bfe_u32 v7, v3, 16, 1
	v_mul_f32_e32 v6, v20, v6
	v_add3_u32 v3, v3, v7, s28
	global_store_short_d16_hi v[14:15], v3, off offset:1024
	v_bfe_u32 v3, v6, 16, 1
	v_add3_u32 v3, v6, v3, s28
	global_store_short_d16_hi v[14:15], v3, off offset:1152
	v_mul_f32_e32 v3, 0x4b800000, v8
	v_cndmask_b32_e32 v3, v8, v3, vcc
	v_rsq_f32_e32 v3, v3
	s_nop 0
	v_mul_f32_e32 v6, 0x45800000, v3
	v_cndmask_b32_e32 v3, v3, v6, vcc
	v_add_u32_e32 v6, 5, v2
	v_mad_i64_i32 v[8:9], s[2:3], v6, s13, v[0:1]
	v_lshl_add_u64 v[8:9], v[8:9], 0, s[30:31]
	v_lshl_add_u64 v[8:9], v[8:9], 0, v[166:167]
	v_lshl_add_u64 v[14:15], v[8:9], 0, s[14:15]
	v_add_co_u32_e32 v8, vcc, s11, v8
	v_mul_f32_e32 v10, v10, v3
	s_nop 0
	v_addc_co_u32_e32 v9, vcc, 0, v9, vcc
	v_mov_b32_e32 v8, v190
	v_ashrrev_i32_e32 v7, 31, v6
	v_mov_b32_e32 v9, v191
	v_mul_f32_e32 v10, v13, v10
	v_mul_f32_e32 v3, v11, v3
	v_mul_f32_e32 v3, v12, v3
	v_lshlrev_b64 v[6:7], 11, v[6:7]
	v_lshl_add_u64 v[6:7], s[94:95], 0, v[6:7]
	v_lshl_add_u64 v[6:7], v[6:7], 0, v[166:167]
	v_lshlrev_b32_e32 v8, 16, v8
	v_mul_f32_e32 v8, 0xbfb8aa3b, v8
	v_lshlrev_b32_e32 v9, 16, v9
	v_exp_f32_e32 v8, v8
	v_mul_f32_e32 v9, 0xbfb8aa3b, v9
	v_exp_f32_e32 v9, v9
	v_add_f32_e32 v8, 1.0, v8
	v_rcp_f32_e32 v8, v8
	v_add_f32_e32 v9, 1.0, v9
	v_rcp_f32_e32 v9, v9
	v_mul_f32_e32 v8, v8, v10
	v_mul_f32_e32 v3, v9, v3
	v_bfe_u32 v9, v8, 16, 1
	v_add3_u32 v8, v8, v9, s28
	global_store_short_d16_hi v[6:7], v8, off offset:1024
	v_bfe_u32 v8, v3, 16, 1
	v_add3_u32 v3, v3, v8, s28
	global_store_short_d16_hi v[6:7], v3, off offset:1152
	v_add_u32_e32 v6, 6, v2
	v_mad_i64_i32 v[14:15], s[2:3], v6, s13, v[0:1]
	v_lshl_add_u64 v[14:15], v[14:15], 0, s[30:31]
	v_lshl_add_u64 v[14:15], v[14:15], 0, v[166:167]
	v_lshl_add_u64 v[16:17], v[14:15], 0, s[14:15]
	v_add_co_u32_e32 v14, vcc, s11, v14
	ds_read_b32 v8, v133
	ds_read_b32 v9, v134 offset:256
	v_addc_co_u32_e32 v15, vcc, 0, v15, vcc
	v_mov_b32_e32 v3, v192
	v_ashrrev_i32_e32 v7, 31, v6
	v_mov_b32_e32 v14, v193
	v_lshlrev_b64 v[6:7], 11, v[6:7]
	v_lshl_add_u64 v[6:7], s[94:95], 0, v[6:7]
	s_waitcnt lgkmcnt(0)
	v_pk_mul_f32 v[10:11], v[8:9], v[8:9]
	v_add_u32_e32 v2, 7, v2
	v_mov_b32_e32 v19, v10
	v_mad_i64_i32 v[0:1], s[2:3], v2, s13, v[0:1]
	v_lshl_add_u64 v[0:1], v[0:1], 0, s[30:31]
	v_lshl_add_u64 v[0:1], v[0:1], 0, v[166:167]
	v_readlane_b32 s2, v255, 28
	v_lshlrev_b32_e32 v3, 16, v3
	v_mul_f32_e32 v3, 0xbfb8aa3b, v3
	v_lshlrev_b32_e32 v14, 16, v14
	v_mul_f32_e32 v14, 0xbfb8aa3b, v14
	v_exp_f32_e32 v14, v14
	v_exp_f32_e32 v3, v3
	v_add_u32_e32 v145, s2, v145
	v_add_u32_e32 v66, s2, v66
	v_add_f32_e32 v14, 1.0, v14
	v_rcp_f32_e32 v20, v14
	v_lshl_add_u64 v[14:15], v[6:7], 0, v[166:167]
	ds_read_b32 v6, v135
	ds_read_b32 v7, v136 offset:256
	v_add_f32_e32 v3, 1.0, v3
	v_rcp_f32_e32 v3, v3
	v_add_u32_e32 v144, s2, v144
	s_waitcnt lgkmcnt(0)
	v_pk_mul_f32 v[16:17], v[6:7], v[6:7]
	s_nop 0
	v_mov_b32_e32 v18, v16
	v_mov_b32_e32 v10, v17
	v_pk_add_f32 v[10:11], v[18:19], v[10:11]
	ds_bpermute_b32 v17, v67, v11
	ds_bpermute_b32 v16, v67, v10
	s_waitcnt lgkmcnt(0)
	v_pk_add_f32 v[10:11], v[10:11], v[16:17]
	ds_bpermute_b32 v17, v68, v11
	ds_bpermute_b32 v16, v68, v10
	s_waitcnt lgkmcnt(0)
	v_pk_add_f32 v[10:11], v[10:11], v[16:17]
	ds_bpermute_b32 v17, v56, v11
	ds_bpermute_b32 v16, v56, v10
	s_waitcnt lgkmcnt(0)
	v_pk_add_f32 v[10:11], v[10:11], v[16:17]
	ds_bpermute_b32 v17, v55, v11
	ds_bpermute_b32 v16, v55, v10
	s_waitcnt lgkmcnt(0)
	v_pk_add_f32 v[10:11], v[10:11], v[16:17]
	ds_bpermute_b32 v17, v54, v11
	ds_bpermute_b32 v16, v54, v10
	s_waitcnt lgkmcnt(0)
	v_pk_add_f32 v[10:11], v[10:11], v[16:17]
	ds_bpermute_b32 v17, v53, v11
	ds_bpermute_b32 v16, v53, v10
	s_waitcnt lgkmcnt(0)
	v_pk_add_f32 v[10:11], v[10:11], v[16:17]
	s_nop 0
	v_pk_fma_f32 v[4:5], v[10:11], s[16:17], v[4:5] op_sel_hi:[1,0,0]
	s_nop 0
	v_mul_f32_e32 v10, 0x4b800000, v5
	v_cmp_gt_f32_e64 s[78:79], s12, v5
	v_cmp_gt_f32_e32 vcc, s12, v4
	s_nop 0
	v_cndmask_b32_e64 v5, v5, v10, s[78:79]
	v_rsq_f32_e32 v5, v5
	s_nop 0
	v_mul_f32_e32 v10, 0x45800000, v5
	v_cndmask_b32_e64 v5, v5, v10, s[78:79]
	v_mul_f32_e32 v8, v8, v5
	v_mul_f32_e32 v8, v13, v8
	v_mul_f32_e32 v3, v3, v8
	v_mul_f32_e32 v5, v9, v5
	v_mul_f32_e32 v5, v12, v5
	v_bfe_u32 v8, v3, 16, 1
	v_mul_f32_e32 v5, v20, v5
	v_add3_u32 v3, v3, v8, s28
	global_store_short_d16_hi v[14:15], v3, off offset:1024
	v_bfe_u32 v3, v5, 16, 1
	v_add3_u32 v3, v5, v3, s28
	global_store_short_d16_hi v[14:15], v3, off offset:1152
	v_mul_f32_e32 v3, 0x4b800000, v4
	v_cndmask_b32_e32 v3, v4, v3, vcc
	v_rsq_f32_e32 v3, v3
	v_lshl_add_u64 v[8:9], v[0:1], 0, s[14:15]
	v_mul_f32_e32 v4, 0x45800000, v3
	v_cndmask_b32_e32 v4, v3, v4, vcc
	v_add_co_u32_e32 v0, vcc, s11, v0
	v_mul_f32_e32 v5, v6, v4
	s_nop 0
	v_addc_co_u32_e32 v1, vcc, 0, v1, vcc
	v_mov_b32_e32 v0, v194
	v_mul_f32_e32 v5, v13, v5
	v_mov_b32_e32 v1, v195
	v_mul_f32_e32 v4, v7, v4
	v_mul_f32_e32 v4, v12, v4
	v_ashrrev_i32_e32 v3, 31, v2
	v_lshlrev_b32_e32 v0, 16, v0
	v_mul_f32_e32 v0, 0xbfb8aa3b, v0
	v_lshlrev_b32_e32 v1, 16, v1
	v_exp_f32_e32 v0, v0
	v_mul_f32_e32 v1, 0xbfb8aa3b, v1
	v_exp_f32_e32 v1, v1
	v_add_f32_e32 v0, 1.0, v0
	v_rcp_f32_e32 v0, v0
	v_add_f32_e32 v1, 1.0, v1
	v_rcp_f32_e32 v1, v1
	v_mul_f32_e32 v0, v0, v5
	v_mul_f32_e32 v4, v1, v4
	v_bfe_u32 v1, v0, 16, 1
	v_add3_u32 v5, v0, v1, s28
	v_lshlrev_b64 v[0:1], 11, v[2:3]
	v_lshl_add_u64 v[0:1], s[94:95], 0, v[0:1]
	v_bfe_u32 v2, v4, 16, 1
	v_lshl_add_u64 v[0:1], v[0:1], 0, v[166:167]
	v_add3_u32 v2, v4, v2, s28
	global_store_short_d16_hi v[0:1], v5, off offset:1024
	global_store_short_d16_hi v[0:1], v2, off offset:1152
	s_barrier
	s_cbranch_scc1 .LBB0_549
